# attention loop: K/V tile loads via SGPR base + per-lane offset (no per-iteration address VALU), LDS waits merged pairwise
# speedup vs baseline: 1.0449x; 1.0088x over previous
.LBB0_1338:
	v_mov_b32_e32 v54, v191
	s_lshl_b32 s97, s4, 8
	s_add_i32 s97, s97, s79
	v_and_b32_e32 v48, 31, v54
	v_or_b32_e32 v0, s97, v48
	v_ashrrev_i32_e32 v50, 3, v54
	v_and_b32_e32 v56, 7, v54
	v_bfe_u32 v49, v54, 5, 1
	v_add_u32_e32 v0, s91, v0
	s_movk_i32 s0, 0xc00
	v_ashrrev_i32_e32 v51, 4, v54
	v_and_b32_e32 v55, 15, v54
	v_add_u32_e32 v9, s91, v50
	v_lshlrev_b32_e32 v52, 3, v56
	v_ashrrev_i32_e32 v1, 31, v0
	v_mad_i64_i32 v[2:3], s[0:1], v0, s0, v[182:183]
	v_lshlrev_b32_e32 v180, 4, v49
	v_add_lshl_u32 v8, v51, s91, 10
	v_lshlrev_b32_e32 v53, 3, v55
	v_lshl_or_b32 v10, v9, 6, v52
	v_add_lshl_u32 v9, v50, s92, 15
	v_lshl_add_u64 v[24:25], v[2:3], 0, v[180:181]
	v_lshlrev_b64 v[0:1], 7, v[0:1]
	v_or3_b32 v8, v8, v53, s92
	v_or3_b32 v12, v9, s91, v52
	v_add_lshl_u32 v234, v50, s92, 11
	v_add_u32_e32 v12, v12, v234
	v_mov_b32_e32 v9, v181
	global_load_dwordx4 v[96:99], v[24:25], off
	global_load_dwordx4 v[100:103], v[24:25], off offset:32
	global_load_dwordx4 v[104:107], v[24:25], off offset:64
	global_load_dwordx4 v[108:111], v[24:25], off offset:96
	global_load_dwordx4 v[112:115], v[24:25], off offset:128
	global_load_dwordx4 v[116:119], v[24:25], off offset:160
	global_load_dwordx4 v[120:123], v[24:25], off offset:192
	global_load_dwordx4 v[124:127], v[24:25], off offset:224
	v_lshl_add_u64 v[2:3], s[62:63], 0, v[0:1]
	v_lshlrev_b32_e32 v4, 5, v49
	v_mov_b32_e32 v5, v181
	v_lshl_add_u64 v[14:15], v[8:9], 1, s[64:65]
	v_add_u32_e32 v8, 0x8000, v8
	v_lshl_add_u64 v[28:29], v[2:3], 0, v[4:5]
	v_lshl_add_u64 v[0:1], s[66:67], 0, v[0:1]
	v_lshl_add_u64 v[8:9], v[8:9], 1, s[64:65]
	v_mov_b32_e32 v11, v181
	v_lshl_add_u64 v[44:45], v[0:1], 0, v[4:5]
	global_load_dwordx4 v[0:3], v[28:29], off offset:16
	global_load_dwordx4 v[4:7], v[28:29], off
	global_load_dwordx4 v[128:131], v[14:15], off
	global_load_dwordx4 v[132:135], v[8:9], off
	v_lshl_add_u64 v[8:9], v[10:11], 1, s[60:61]
	v_mov_b32_e32 v13, v181
	v_lshl_add_u64 v[10:11], v[12:13], 1, s[68:69]
	global_load_dwordx4 v[136:139], v[8:9], off
	global_load_dwordx4 v[140:143], v[10:11], off
	v_add_u32_e32 v8, 0x220000, v12
	v_mov_b32_e32 v9, v181
	v_lshl_add_u64 v[8:9], v[8:9], 1, s[68:69]
	global_load_dwordx4 v[144:147], v[8:9], off
	s_nop 0
	global_load_dwordx4 v[8:11], v[44:45], off offset:16
	global_load_dwordx4 v[20:23], v[44:45], off
	global_load_dwordx4 v[12:15], v[24:25], off offset:256
	global_load_dwordx4 v[32:35], v[24:25], off offset:288
	global_load_dwordx4 v[16:19], v[24:25], off offset:320
	global_load_dwordx4 v[36:39], v[24:25], off offset:352
	s_nop 0
	global_load_dwordx4 v[24:27], v[28:29], off offset:80
	global_load_dwordx4 v[40:43], v[28:29], off offset:64
	s_nop 0
	global_load_dwordx4 v[28:31], v[44:45], off offset:80
	s_nop 0
	global_load_dwordx4 v[44:47], v[44:45], off offset:64
	v_lshlrev_b32_e32 v57, 3, v54
	v_mul_lo_u32 v58, v51, s82
	v_lshlrev_b32_e32 v54, 4, v56
	v_mul_lo_u32 v56, v50, s83
	v_lshl_add_u32 v194, v55, 4, v58
	v_and_b32_e32 v55, 0x60, v54
	v_and_b32_e32 v57, 8, v57
	v_mad_u64_u32 v[184:185], s[0:1], v50, s82, v[54:55]
	v_add_u32_e32 v54, 0, v56
	v_add3_u32 v185, v54, v57, v55
	v_add_u32_e32 v56, 0, v194
	v_add_u32_e32 v54, 0xc800, v185
	v_add_u32_e32 v58, 0, v184
	v_add_u32_e32 v55, 0xe800, v185
	s_cmp_lt_i32 s4, 0
	s_mov_b32 s52, 0
	s_waitcnt vmcnt(0)
	ds_write_b128 v56, v[128:131]
	ds_write_b128 v56, v[132:135] offset:12800
	ds_write_b128 v58, v[136:139] offset:256
	ds_write2_b64 v54, v[140:141], v[142:143] offset1:2
	ds_write2_b64 v55, v[144:145], v[146:147] offset0:128 offset1:130
	v_mad_u32_u24 v54, v48, s83, 0
	v_add_u32_e32 v195, v54, v180
	v_add_u32_e32 v173, 0xc800, v195
	s_waitcnt lgkmcnt(0)
	s_barrier
	s_cbranch_scc1 .LBB0_1331
	v_lshlrev_b32_e32 v55, 8, v48
	v_add3_u32 v196, v54, v55, v180
	v_and_b32_e32 v55, 0xffff0000, v36
	v_lshlrev_b32_e32 v54, 16, v36
	v_and_b32_e32 v57, 0xffff0000, v32
	v_lshlrev_b32_e32 v56, 16, v32
	v_pk_mul_f32 v[58:59], v[44:45], v[56:57]
	v_pk_mul_f32 v[44:45], v[44:45], v[54:55]
	v_pk_fma_f32 v[58:59], v[40:41], v[54:55], v[58:59]
	v_pk_fma_f32 v[40:41], v[40:41], v[56:57], v[44:45] neg_lo:[0,0,1] neg_hi:[0,0,1]
	v_lshlrev_b32_e32 v36, 16, v33
	v_cvt_pk_bf16_f32 v152, v40, v41
	v_and_b32_e32 v41, 0xffff0000, v37
	v_lshlrev_b32_e32 v40, 16, v37
	v_and_b32_e32 v37, 0xffff0000, v33
	v_pk_mul_f32 v[32:33], v[46:47], v[36:37]
	s_lshl_b32 s53, s4, 2
	v_pk_fma_f32 v[32:33], v[42:43], v[40:41], v[32:33]
	v_mov_b32_e32 v200, 0
	v_cvt_pk_bf16_f32 v149, v32, v33
	v_pk_mul_f32 v[32:33], v[46:47], v[40:41]
	s_add_i32 s53, s53, 4
	v_pk_fma_f32 v[32:33], v[42:43], v[36:37], v[32:33] neg_lo:[0,0,1] neg_hi:[0,0,1]
	v_and_b32_e32 v37, 0xffff0000, v34
	v_cvt_pk_bf16_f32 v153, v32, v33
	v_and_b32_e32 v33, 0xffff0000, v38
	v_lshlrev_b32_e32 v32, 16, v38
	v_lshlrev_b32_e32 v36, 16, v34
	v_pk_mul_f32 v[40:41], v[28:29], v[36:37]
	v_pk_mul_f32 v[28:29], v[28:29], v[32:33]
	v_pk_fma_f32 v[40:41], v[24:25], v[32:33], v[40:41]
	v_pk_fma_f32 v[24:25], v[24:25], v[36:37], v[28:29] neg_lo:[0,0,1] neg_hi:[0,0,1]
	v_and_b32_e32 v29, 0xffff0000, v35
	v_lshlrev_b32_e32 v28, 16, v35
	v_cvt_pk_bf16_f32 v154, v24, v25
	v_and_b32_e32 v25, 0xffff0000, v39
	v_lshlrev_b32_e32 v24, 16, v39
	v_pk_mul_f32 v[32:33], v[30:31], v[28:29]
	v_cvt_pk_bf16_f32 v148, v58, v59
	v_pk_fma_f32 v[32:33], v[26:27], v[24:25], v[32:33]
	v_pk_mul_f32 v[24:25], v[30:31], v[24:25]
	v_cvt_pk_bf16_f32 v150, v40, v41
	v_pk_fma_f32 v[24:25], v[26:27], v[28:29], v[24:25] neg_lo:[0,0,1] neg_hi:[0,0,1]
	v_and_b32_e32 v27, 0xffff0000, v12
	v_cvt_pk_bf16_f32 v155, v24, v25
	v_and_b32_e32 v25, 0xffff0000, v16
	v_lshlrev_b32_e32 v24, 16, v16
	v_lshlrev_b32_e32 v26, 16, v12
	v_pk_mul_f32 v[28:29], v[20:21], v[26:27]
	v_pk_mul_f32 v[20:21], v[20:21], v[24:25]
	v_pk_fma_f32 v[28:29], v[4:5], v[24:25], v[28:29]
	v_pk_fma_f32 v[4:5], v[4:5], v[26:27], v[20:21] neg_lo:[0,0,1] neg_hi:[0,0,1]
	v_lshlrev_b32_e32 v16, 16, v13
	v_cvt_pk_bf16_f32 v160, v4, v5
	v_and_b32_e32 v5, 0xffff0000, v17
	v_lshlrev_b32_e32 v4, 16, v17
	v_and_b32_e32 v17, 0xffff0000, v13
	v_pk_mul_f32 v[12:13], v[22:23], v[16:17]
	v_cvt_pk_bf16_f32 v151, v32, v33
	v_pk_fma_f32 v[12:13], v[6:7], v[4:5], v[12:13]
	v_pk_mul_f32 v[4:5], v[22:23], v[4:5]
	v_cvt_pk_bf16_f32 v157, v12, v13
	v_pk_fma_f32 v[4:5], v[6:7], v[16:17], v[4:5] neg_lo:[0,0,1] neg_hi:[0,0,1]
	v_and_b32_e32 v7, 0xffff0000, v14
	v_lshlrev_b32_e32 v6, 16, v14
	v_cvt_pk_bf16_f32 v161, v4, v5
	v_and_b32_e32 v5, 0xffff0000, v18
	v_lshlrev_b32_e32 v4, 16, v18
	v_pk_mul_f32 v[12:13], v[8:9], v[6:7]
	v_cvt_pk_bf16_f32 v156, v28, v29
	v_pk_fma_f32 v[12:13], v[0:1], v[4:5], v[12:13]
	v_pk_mul_f32 v[4:5], v[8:9], v[4:5]
	v_cvt_pk_bf16_f32 v158, v12, v13
	v_pk_fma_f32 v[0:1], v[0:1], v[6:7], v[4:5] neg_lo:[0,0,1] neg_hi:[0,0,1]
	v_and_b32_e32 v5, 0xffff0000, v15
	v_lshlrev_b32_e32 v4, 16, v15
	v_cvt_pk_bf16_f32 v162, v0, v1
	v_and_b32_e32 v1, 0xffff0000, v19
	v_lshlrev_b32_e32 v0, 16, v19
	v_pk_mul_f32 v[6:7], v[10:11], v[4:5]
	v_mov_b32_e32 v199, 0xf149f2ca
	v_pk_fma_f32 v[6:7], v[2:3], v[0:1], v[6:7]
	v_pk_mul_f32 v[0:1], v[10:11], v[0:1]
	v_cvt_pk_bf16_f32 v159, v6, v7
	v_pk_fma_f32 v[0:1], v[2:3], v[4:5], v[0:1] neg_lo:[0,0,1] neg_hi:[0,0,1]
	s_mov_b32 s33, 63
	v_cvt_pk_bf16_f32 v163, v0, v1
	v_lshlrev_b32_e32 v1, 10, v51
	v_lshlrev_b32_e32 v0, 2, v49
	v_add3_u32 v186, s93, v1, v53
	v_add_u32_e32 v1, s97, v48
	v_sub_u32_e32 v197, v1, v0
	v_lshlrev_b32_e32 v0, 6, v50
	v_add3_u32 v188, s94, v0, v52
	v_lshlrev_b32_e32 v0, 15, v50
	v_add3_u32 v198, s95, v0, v52
	v_add_lshl_u32 v234, v50, s92, 11
	v_add_u32_e32 v198, v198, v234
	v_mov_b32_e32 v64, 0
	v_mov_b32_e32 v65, 0
	v_mov_b32_e32 v66, 0
	v_mov_b32_e32 v67, 0
	v_mov_b32_e32 v68, 0
	v_mov_b32_e32 v69, 0
	v_mov_b32_e32 v70, 0
	v_mov_b32_e32 v71, 0
	s_mov_b32 s0, 0
	v_mov_b32_e32 v0, 0
	v_mov_b32_e32 v1, v200
	v_mov_b32_e32 v2, v200
	v_mov_b32_e32 v3, v200
	v_mov_b32_e32 v4, v200
	v_mov_b32_e32 v5, v200
	v_mov_b32_e32 v6, v200
	v_mov_b32_e32 v7, v200
	v_mov_b32_e32 v8, v200
	v_mov_b32_e32 v9, v200
	v_mov_b32_e32 v10, v200
	v_mov_b32_e32 v11, v200
	v_mov_b32_e32 v12, v200
	v_mov_b32_e32 v13, v200
	v_mov_b32_e32 v14, v200
	v_mov_b32_e32 v15, v200
	v_mov_b32_e32 v16, 0
	v_mov_b32_e32 v17, v200
	v_mov_b32_e32 v18, v200
	v_mov_b32_e32 v19, v200
	v_mov_b32_e32 v20, v200
	v_mov_b32_e32 v21, v200
	v_mov_b32_e32 v22, v200
	v_mov_b32_e32 v23, v200
	v_mov_b32_e32 v24, v200
	v_mov_b32_e32 v25, v200
	v_mov_b32_e32 v26, v200
	v_mov_b32_e32 v27, v200
	v_mov_b32_e32 v28, v200
	v_mov_b32_e32 v29, v200
	v_mov_b32_e32 v30, v200
	v_mov_b32_e32 v31, v200
	v_mov_b32_e32 v32, 0
	v_mov_b32_e32 v33, v200
	v_mov_b32_e32 v34, v200
	v_mov_b32_e32 v35, v200
	v_mov_b32_e32 v36, v200
	v_mov_b32_e32 v37, v200
	v_mov_b32_e32 v38, v200
	v_mov_b32_e32 v39, v200
	v_mov_b32_e32 v40, v200
	v_mov_b32_e32 v41, v200
	v_mov_b32_e32 v42, v200
	v_mov_b32_e32 v43, v200
	v_mov_b32_e32 v44, v200
	v_mov_b32_e32 v45, v200
	v_mov_b32_e32 v46, v200
	v_mov_b32_e32 v47, v200
	v_mov_b32_e32 v48, 0
	v_mov_b32_e32 v49, v200
	v_mov_b32_e32 v50, v200
	v_mov_b32_e32 v51, v200
	v_mov_b32_e32 v52, v200
	v_mov_b32_e32 v53, v200
	v_mov_b32_e32 v54, v200
	v_mov_b32_e32 v55, v200
	v_mov_b32_e32 v56, v200
	v_mov_b32_e32 v57, v200
	v_mov_b32_e32 v58, v200
	v_mov_b32_e32 v59, v200
	v_mov_b32_e32 v60, v200
	v_mov_b32_e32 v61, v200
	v_mov_b32_e32 v62, v200
	v_mov_b32_e32 v63, v200
	v_mov_b32_e32 v187, 0
	v_mov_b32_e32 v189, 0
	v_xor_b32_e32 v246, 32, v193
	v_lshlrev_b32_e32 v246, 2, v246
	v_mov_b32_e32 v64, 0xff61b1e6
	v_mov_b32_e32 v65, v64
	v_mov_b32_e32 v66, v64
	v_mov_b32_e32 v67, v64
	v_mov_b32_e32 v68, v64
	v_mov_b32_e32 v69, v64
	v_mov_b32_e32 v70, v64
	v_mov_b32_e32 v71, v64
	v_mov_b32_e32 v72, v64
	v_mov_b32_e32 v73, v64
	v_mov_b32_e32 v74, v64
	v_mov_b32_e32 v75, v64
	v_mov_b32_e32 v76, v64
	v_mov_b32_e32 v77, v64
	v_mov_b32_e32 v78, v64
	v_mov_b32_e32 v79, v64
	v_add_u32_e32 v201, 0xffff8000, v186
	v_lshlrev_b32_e32 v201, 1, v201
	v_lshlrev_b32_e32 v230, 1, v186
	v_lshlrev_b32_e32 v231, 1, v188
	v_add_u32_e32 v232, 64, v198
	v_lshlrev_b32_e32 v232, 1, v232
	v_add_u32_e32 v233, 0x440000, v232
	s_mov_b64 s[20:21], s[64:65]
	s_mov_b64 s[22:23], s[60:61]
	s_mov_b64 s[24:25], s[68:69]
	global_load_dwordx4 v[128:131], v201, s[20:21]
	global_load_dwordx4 v[132:135], v230, s[20:21]
	global_load_dwordx4 v[136:139], v231, s[22:23]
	global_load_dwordx4 v[140:143], v232, s[24:25]
	global_load_dwordx4 v[144:147], v233, s[24:25]
.LBB0_1340:
	s_add_i32 s54, s0, 1
	s_bitcmp1_b32 s0, 0
	s_cselect_b32 s4, 0x6400, 0
	v_add_u32_e32 v174, s4, v196
	s_mul_i32 s4, s52, 0x4800
	v_add_u32_e32 v234, s4, v195
	ds_read_b128 v[202:205], v174 offset:0
	ds_read_b128 v[206:209], v174 offset:32
	ds_read_b128 v[210:213], v174 offset:64
	ds_read_b128 v[214:217], v174 offset:96
	ds_read_b128 v[218:221], v174 offset:128
	ds_read_b128 v[222:225], v174 offset:160
	v_fma_f32 v64, v64, s84, -v199
	v_exp_f32_e32 v64, v64
	v_fma_f32 v65, v65, s84, -v199
	v_exp_f32_e32 v65, v65
	v_add_f32_e32 v200, v200, v64
	v_fma_f32 v66, v66, s84, -v199
	v_exp_f32_e32 v66, v66
	v_add_f32_e32 v200, v200, v65
	s_waitcnt lgkmcnt(4)
	v_mfma_f32_32x32x16_bf16 v[80:95], v[202:205], v[96:99], 0
	ds_read_b128 v[202:205], v174 offset:192
	v_fma_f32 v67, v67, s84, -v199
	v_exp_f32_e32 v67, v67
	v_add_f32_e32 v200, v200, v66
	v_fma_f32 v68, v68, s84, -v199
	v_mfma_f32_32x32x16_bf16 v[80:95], v[206:209], v[100:103], v[80:95]
	ds_read_b128 v[206:209], v174 offset:224
	v_exp_f32_e32 v68, v68
	v_add_f32_e32 v200, v200, v67
	v_fma_f32 v69, v69, s84, -v199
	v_exp_f32_e32 v69, v69
	s_waitcnt lgkmcnt(4)
	v_mfma_f32_32x32x16_bf16 v[80:95], v[210:213], v[104:107], v[80:95]
	ds_read_b128 v[210:213], v174 offset:256
	v_add_f32_e32 v200, v200, v68
	v_fma_f32 v70, v70, s84, -v199
	v_exp_f32_e32 v70, v70
	v_add_f32_e32 v200, v200, v69
	v_mfma_f32_32x32x16_bf16 v[80:95], v[214:217], v[108:111], v[80:95]
	ds_read_b128 v[214:217], v174 offset:288
	v_fma_f32 v71, v71, s84, -v199
	v_exp_f32_e32 v71, v71
	v_add_f32_e32 v200, v200, v70
	v_fma_f32 v72, v72, s84, -v199
	s_waitcnt lgkmcnt(4)
	v_mfma_f32_32x32x16_bf16 v[80:95], v[218:221], v[112:115], v[80:95]
	ds_read_b128 v[218:221], v174 offset:320
	v_exp_f32_e32 v72, v72
	v_add_f32_e32 v200, v200, v71
	v_fma_f32 v73, v73, s84, -v199
	v_exp_f32_e32 v73, v73
	v_mfma_f32_32x32x16_bf16 v[80:95], v[222:225], v[116:119], v[80:95]
	ds_read_b128 v[222:225], v174 offset:352
	v_add_f32_e32 v200, v200, v72
	v_fma_f32 v74, v74, s84, -v199
	v_exp_f32_e32 v74, v74
	v_add_f32_e32 v200, v200, v73
	s_waitcnt lgkmcnt(4)
	v_mfma_f32_32x32x16_bf16 v[80:95], v[202:205], v[120:123], v[80:95]
	ds_read_b128 v[164:167], v173 offset:0
	v_fma_f32 v75, v75, s84, -v199
	v_exp_f32_e32 v75, v75
	v_add_f32_e32 v200, v200, v74
	v_fma_f32 v76, v76, s84, -v199
	v_mfma_f32_32x32x16_bf16 v[80:95], v[206:209], v[124:127], v[80:95]
	ds_read_b128 v[168:171], v173 offset:4608
	v_exp_f32_e32 v76, v76
	v_add_f32_e32 v200, v200, v75
	v_fma_f32 v77, v77, s84, -v199
	v_exp_f32_e32 v77, v77
	s_waitcnt lgkmcnt(4)
	v_mfma_f32_32x32x16_bf16 v[80:95], v[210:213], v[160:163], v[80:95]
	ds_read_b128 v[176:179], v173 offset:9216
	v_add_f32_e32 v200, v200, v76
	v_fma_f32 v78, v78, s84, -v199
	v_exp_f32_e32 v78, v78
	v_add_f32_e32 v200, v200, v77
	v_mfma_f32_32x32x16_bf16 v[80:95], v[214:217], v[152:155], v[80:95]
	ds_read_b128 v[226:229], v173 offset:13824
	v_fma_f32 v79, v79, s84, -v199
	v_exp_f32_e32 v79, v79
	v_add_f32_e32 v200, v200, v78
	v_add_f32_e32 v200, v200, v79
	s_waitcnt lgkmcnt(4)
	v_mfma_f32_32x32x16_bf16 v[80:95], v[218:221], v[156:159], v[80:95]
	v_cvt_pk_bf16_f32 v64, v64, v65
	v_cvt_pk_bf16_f32 v65, v66, v67
	v_cvt_pk_bf16_f32 v66, v68, v69
	v_cvt_pk_bf16_f32 v67, v70, v71
	v_mfma_f32_32x32x16_bf16 v[80:95], v[222:225], v[148:151], v[80:95]
	v_cvt_pk_bf16_f32 v68, v72, v73
	v_cvt_pk_bf16_f32 v69, v74, v75
	v_cvt_pk_bf16_f32 v70, v76, v77
	v_cvt_pk_bf16_f32 v71, v78, v79
	s_waitcnt lgkmcnt(2)
	v_mfma_f32_32x32x16_bf16 v[48:63], v[164:167], v[64:67], v[48:63]
	ds_read_b128 v[164:167], v173 offset:32
	v_mfma_f32_32x32x16_bf16 v[32:47], v[168:171], v[64:67], v[32:47]
	ds_read_b128 v[168:171], v173 offset:4640
	s_waitcnt lgkmcnt(2)
	v_mfma_f32_32x32x16_bf16 v[16:31], v[176:179], v[64:67], v[16:31]
	ds_read_b128 v[176:179], v173 offset:9248
	v_mfma_f32_32x32x16_bf16 v[0:15], v[226:229], v[64:67], v[0:15]
	ds_read_b128 v[226:229], v173 offset:13856
	ds_read_b128 v[202:205], v174 offset:12800
	ds_read_b128 v[206:209], v174 offset:12832
	ds_read_b128 v[210:213], v174 offset:12864
	ds_read_b128 v[214:217], v174 offset:12896
	ds_read_b128 v[218:221], v174 offset:12928
	ds_read_b128 v[222:225], v174 offset:12960
	s_cmp_gt_i32 s33, s97
	s_cbranch_scc1 .Lat_mask_a
.Lat_mask_a_ret:
	s_waitcnt lgkmcnt(8)
	v_mfma_f32_32x32x16_bf16 v[48:63], v[164:167], v[68:71], v[48:63]
	v_add_f32_e32 v175, 0x41000000, v199
	v_max3_f32 v172, v80, v81, v82
	v_max3_f32 v172, v172, v83, v84
	v_mfma_f32_32x32x16_bf16 v[32:47], v[168:171], v[68:71], v[32:47]
	v_max3_f32 v172, v172, v85, v86
	v_max3_f32 v172, v172, v87, v88
	v_max3_f32 v172, v172, v89, v90
	s_waitcnt lgkmcnt(6)
	v_mfma_f32_32x32x16_bf16 v[16:31], v[176:179], v[68:71], v[16:31]
	v_max3_f32 v172, v172, v91, v92
	v_max3_f32 v172, v172, v93, v94
	v_max_f32_e32 v172, v172, v95
	v_mfma_f32_32x32x16_bf16 v[0:15], v[226:229], v[68:71], v[0:15]
	v_mul_f32_e32 v172, 0x3dd53b94, v172
	v_cmp_gt_f32_e32 vcc, v172, v175
	s_cmp_lg_u64 vcc, 0
	s_cbranch_scc1 .Lat_resc_a
.Lat_resc_a_ret:
	v_fma_f32 v80, v80, s84, -v199
	v_exp_f32_e32 v80, v80
	v_fma_f32 v81, v81, s84, -v199
	v_exp_f32_e32 v81, v81
	v_add_f32_e32 v200, v200, v80
	v_fma_f32 v82, v82, s84, -v199
	v_exp_f32_e32 v82, v82
	v_add_f32_e32 v200, v200, v81
	s_waitcnt lgkmcnt(4)
	v_mfma_f32_32x32x16_bf16 v[64:79], v[202:205], v[96:99], 0
	ds_read_b128 v[202:205], v174 offset:12992
	v_fma_f32 v83, v83, s84, -v199
	v_exp_f32_e32 v83, v83
	v_add_f32_e32 v200, v200, v82
	v_fma_f32 v84, v84, s84, -v199
	v_mfma_f32_32x32x16_bf16 v[64:79], v[206:209], v[100:103], v[64:79]
	ds_read_b128 v[206:209], v174 offset:13024
	v_exp_f32_e32 v84, v84
	v_add_f32_e32 v200, v200, v83
	v_fma_f32 v85, v85, s84, -v199
	v_exp_f32_e32 v85, v85
	s_waitcnt lgkmcnt(4)
	v_mfma_f32_32x32x16_bf16 v[64:79], v[210:213], v[104:107], v[64:79]
	ds_read_b128 v[210:213], v174 offset:13056
	v_add_f32_e32 v200, v200, v84
	v_fma_f32 v86, v86, s84, -v199
	v_exp_f32_e32 v86, v86
	v_add_f32_e32 v200, v200, v85
	v_mfma_f32_32x32x16_bf16 v[64:79], v[214:217], v[108:111], v[64:79]
	ds_read_b128 v[214:217], v174 offset:13088
	v_fma_f32 v87, v87, s84, -v199
	v_exp_f32_e32 v87, v87
	v_add_f32_e32 v200, v200, v86
	v_fma_f32 v88, v88, s84, -v199
	s_waitcnt lgkmcnt(4)
	v_mfma_f32_32x32x16_bf16 v[64:79], v[218:221], v[112:115], v[64:79]
	ds_read_b128 v[218:221], v174 offset:13120
	v_exp_f32_e32 v88, v88
	v_add_f32_e32 v200, v200, v87
	v_fma_f32 v89, v89, s84, -v199
	v_exp_f32_e32 v89, v89
	v_mfma_f32_32x32x16_bf16 v[64:79], v[222:225], v[116:119], v[64:79]
	ds_read_b128 v[222:225], v174 offset:13152
	v_add_f32_e32 v200, v200, v88
	v_fma_f32 v90, v90, s84, -v199
	v_exp_f32_e32 v90, v90
	v_add_f32_e32 v200, v200, v89
	s_waitcnt lgkmcnt(4)
	v_mfma_f32_32x32x16_bf16 v[64:79], v[202:205], v[120:123], v[64:79]
	ds_read_b128 v[164:167], v234 offset:51200
	v_fma_f32 v91, v91, s84, -v199
	v_exp_f32_e32 v91, v91
	v_add_f32_e32 v200, v200, v90
	v_fma_f32 v92, v92, s84, -v199
	v_mfma_f32_32x32x16_bf16 v[64:79], v[206:209], v[124:127], v[64:79]
	ds_read_b128 v[168:171], v234 offset:55808
	v_exp_f32_e32 v92, v92
	v_add_f32_e32 v200, v200, v91
	v_fma_f32 v93, v93, s84, -v199
	v_exp_f32_e32 v93, v93
	s_waitcnt lgkmcnt(4)
	v_mfma_f32_32x32x16_bf16 v[64:79], v[210:213], v[160:163], v[64:79]
	ds_read_b128 v[176:179], v234 offset:60416
	v_add_f32_e32 v200, v200, v92
	v_fma_f32 v94, v94, s84, -v199
	v_exp_f32_e32 v94, v94
	v_add_f32_e32 v200, v200, v93
	v_mfma_f32_32x32x16_bf16 v[64:79], v[214:217], v[152:155], v[64:79]
	ds_read_b128 v[226:229], v234 offset:65024
	v_fma_f32 v95, v95, s84, -v199
	v_exp_f32_e32 v95, v95
	v_add_f32_e32 v200, v200, v94
	v_add_f32_e32 v200, v200, v95
	s_waitcnt lgkmcnt(4)
	v_mfma_f32_32x32x16_bf16 v[64:79], v[218:221], v[156:159], v[64:79]
	v_cvt_pk_bf16_f32 v80, v80, v81
	v_cvt_pk_bf16_f32 v81, v82, v83
	v_cvt_pk_bf16_f32 v82, v84, v85
	v_cvt_pk_bf16_f32 v83, v86, v87
	v_mfma_f32_32x32x16_bf16 v[64:79], v[222:225], v[148:151], v[64:79]
	v_cvt_pk_bf16_f32 v84, v88, v89
	v_cvt_pk_bf16_f32 v85, v90, v91
	v_cvt_pk_bf16_f32 v86, v92, v93
	v_cvt_pk_bf16_f32 v87, v94, v95
	s_waitcnt lgkmcnt(2)
	v_mfma_f32_32x32x16_bf16 v[48:63], v[164:167], v[80:83], v[48:63]
	ds_read_b128 v[164:167], v234 offset:51232
	v_mfma_f32_32x32x16_bf16 v[32:47], v[168:171], v[80:83], v[32:47]
	ds_read_b128 v[168:171], v234 offset:55840
	s_waitcnt lgkmcnt(2)
	v_mfma_f32_32x32x16_bf16 v[16:31], v[176:179], v[80:83], v[16:31]
	ds_read_b128 v[176:179], v234 offset:60448
	v_mfma_f32_32x32x16_bf16 v[0:15], v[226:229], v[80:83], v[0:15]
	ds_read_b128 v[226:229], v234 offset:65056
	s_cmp_gt_i32 s33, s97
	s_cbranch_scc1 .Lat_mask_b
.Lat_mask_b_ret:
	s_waitcnt lgkmcnt(2)
	v_mfma_f32_32x32x16_bf16 v[48:63], v[164:167], v[84:87], v[48:63]
	v_add_f32_e32 v175, 0x41000000, v199
	v_max3_f32 v172, v64, v65, v66
	v_max3_f32 v172, v172, v67, v68
	v_mfma_f32_32x32x16_bf16 v[32:47], v[168:171], v[84:87], v[32:47]
	v_max3_f32 v172, v172, v69, v70
	v_max3_f32 v172, v172, v71, v72
	v_max3_f32 v172, v172, v73, v74
	s_waitcnt lgkmcnt(0)
	v_mfma_f32_32x32x16_bf16 v[16:31], v[176:179], v[84:87], v[16:31]
	v_max3_f32 v172, v172, v75, v76
	v_max3_f32 v172, v172, v77, v78
	v_max_f32_e32 v172, v172, v79
	v_mfma_f32_32x32x16_bf16 v[0:15], v[226:229], v[84:87], v[0:15]
	v_mul_f32_e32 v172, 0x3dd53b94, v172
	v_cmp_gt_f32_e32 vcc, v172, v175
	s_cmp_lg_u64 vcc, 0
	s_cbranch_scc1 .Lat_resc_b

.Lat_skip_st:
	s_add_i32 s4, s54, 1
	s_cmp_lt_i32 s4, s53
	s_cbranch_scc0 .Lat_skip_ld
	s_add_u32 s20, s20, 0x20000
	s_addc_u32 s21, s21, 0
	s_add_u32 s22, s22, 0x2000
	s_addc_u32 s23, s23, 0
	s_add_u32 s24, s24, 0x80
	s_addc_u32 s25, s25, 0
	global_load_dwordx4 v[128:131], v201, s[20:21]
	global_load_dwordx4 v[132:135], v230, s[20:21]
	global_load_dwordx4 v[136:139], v231, s[22:23]
	global_load_dwordx4 v[140:143], v232, s[24:25]
	global_load_dwordx4 v[144:147], v233, s[24:25]
